# all five GEMM main loops: LDS-DMA via scalar base + constant 32-bit lane offsets, bases and M0 advanced on the scalar unit (no per-slice vector address ops)
# speedup vs baseline: 1.0266x; 1.0095x over previous
.LBB0_115:
	s_andn2_b64 vcc, exec, s[22:23]
	s_cbranch_vccnz .LBB0_138
	v_readlane_b32 s22, v254, 44
	v_readlane_b32 s23, v254, 45
	s_andn2_b64 vcc, exec, s[22:23]
	s_cbranch_vccnz .LBB0_138
	v_mov_b32_e32 v8, v202
	v_readlane_b32 s8, v254, 48
	v_bfe_u32 v135, v8, 4, 2
	v_bfe_u32 v4, v8, 2, 4
	v_ashrrev_i32_e32 v136, 6, v8
	v_bitop3_b32 v0, v135, v8, 3 bitop3:0x78
	v_or_b32_e32 v9, s8, v4
	v_readlane_b32 s8, v254, 46
	v_lshlrev_b32_e32 v0, 4, v0
	v_cmp_gt_i32_e32 vcc, 16, v136
	v_or_b32_e32 v10, s8, v4
	v_lshl_add_u64 v[2:3], s[20:21], 0, v[0:1]
	v_lshl_add_u64 v[4:5], s[46:47], 0, v[0:1]
	v_lshlrev_b32_e32 v0, 4, v136
	v_cndmask_b32_e32 v11, v9, v10, vcc
	v_cndmask_b32_e32 v7, v3, v5, vcc
	v_cndmask_b32_e32 v6, v2, v4, vcc
	v_add_u32_e32 v11, v11, v0
	v_cmp_gt_i32_e32 vcc, 8, v136
	v_mad_i64_i32 v[126:127], s[20:21], v11, s5, v[6:7]
	s_nop 0
	v_cndmask_b32_e32 v11, v9, v10, vcc
	s_movk_i32 s8, 0x80
	v_cndmask_b32_e32 v7, v3, v5, vcc
	v_cndmask_b32_e32 v6, v2, v4, vcc
	v_add3_u32 v11, v0, v11, s8
	v_cmp_gt_i32_e32 vcc, 0, v136
	v_mad_i64_i32 v[128:129], s[20:21], v11, s5, v[6:7]
	s_nop 0
	v_cndmask_b32_e32 v6, v9, v10, vcc
	s_movk_i32 s8, 0x100
	v_and_b32_e32 v134, 63, v8
	v_cndmask_b32_e32 v3, v3, v5, vcc
	v_cndmask_b32_e32 v2, v2, v4, vcc
	v_add3_u32 v0, v0, v6, s8
	v_mad_i64_i32 v[130:131], s[20:21], v0, s5, v[2:3]
	v_lshlrev_b32_e32 v0, 4, v134
	v_lshl_or_b32 v137, v136, 10, v0
	v_add_u32_e32 v0, 0x2000, v137
	v_readfirstlane_b32 s8, v137
	s_mov_b32 m0, s8
	v_readfirstlane_b32 s8, v0
	v_add_u32_e32 v0, 0x4000, v137
	s_barrier
	global_load_lds_dwordx4 v[126:127], off
	s_mov_b32 m0, s8
	v_readfirstlane_b32 s8, v0
	v_add_u32_e32 v0, 0x6000, v137
	global_load_lds_dwordx4 v[128:129], off
	s_mov_b32 m0, s8
	v_readfirstlane_b32 s8, v0
	v_add_u32_e32 v0, 0x8000, v137
	global_load_lds_dwordx4 v[130:131], off
	v_lshl_add_u64 v[2:3], v[126:127], 0, 64
	s_mov_b32 m0, s8
	v_readfirstlane_b32 s8, v0
	v_add_u32_e32 v0, 0xa000, v137
	global_load_lds_dwordx4 v[2:3], off
	v_lshl_add_u64 v[2:3], v[128:129], 0, 64
	s_mov_b32 m0, s8
	v_readfirstlane_b32 s8, v0
	v_add_u32_e32 v0, 0xc000, v137
	global_load_lds_dwordx4 v[2:3], off
	v_lshl_add_u64 v[2:3], v[130:131], 0, 64
	s_mov_b32 m0, s8
	v_readfirstlane_b32 s8, v0
	v_add_u32_e32 v0, 0xe000, v137
	global_load_lds_dwordx4 v[2:3], off
	v_lshl_add_u64 v[2:3], v[126:127], 0, s[10:11]
	s_mov_b32 m0, s8
	v_readfirstlane_b32 s8, v0
	v_add_u32_e32 v0, 0x10000, v137
	global_load_lds_dwordx4 v[2:3], off
	v_lshl_add_u64 v[2:3], v[128:129], 0, s[10:11]
	s_mov_b32 m0, s8
	v_readfirstlane_b32 s8, v0
	global_load_lds_dwordx4 v[2:3], off
	v_lshl_add_u64 v[2:3], v[130:131], 0, s[10:11]
	s_mov_b32 m0, s8
	v_and_b32_e32 v138, 15, v8
	global_load_lds_dwordx4 v[2:3], off
	v_readfirstlane_b32 s90, v126
	v_readfirstlane_b32 s91, v127
	v_readfirstlane_b32 s92, v130
	v_readfirstlane_b32 s93, v131
	v_readfirstlane_b32 s88, v137
	s_nop 1
	v_subrev_u32_e32 v126, s90, v126
	v_subrev_u32_e32 v128, s90, v128
	v_subrev_u32_e32 v130, s92, v130
	s_add_u32 s90, s90, 0xc0
	s_addc_u32 s91, s91, 0
	s_add_u32 s92, s92, 0xc0
	s_addc_u32 s93, s93, 0
	v_bfe_u32 v2, v8, 2, 2
	v_and_b32_e32 v139, 1, v136
	v_xor_b32_e32 v2, v135, v2
	v_lshlrev_b32_e32 v3, 6, v138
	v_ashrrev_i32_e32 v0, 7, v8
	v_lshl_or_b32 v2, v2, 4, v3
	v_lshlrev_b32_e32 v3, 12, v139
	s_movk_i32 s8, 0x4000
	s_waitcnt vmcnt(6)
	v_lshl_or_b32 v140, v0, 12, v2
	v_or3_b32 v141, v3, v2, s8
	s_waitcnt lgkmcnt(0)
	s_barrier
	ds_read_b128 v[2:5], v140
	ds_read_b128 v[6:9], v140 offset:1024
	ds_read_b128 v[10:13], v140 offset:2048
	ds_read_b128 v[14:17], v140 offset:3072
	ds_read_b128 v[26:29], v141
	ds_read_b128 v[22:25], v141 offset:1024
	v_cmp_lt_i32_e32 vcc, 3, v136
	s_and_saveexec_b64 s[20:21], vcc
	s_cbranch_execz .LBB0_119
	s_barrier

.LBB0_125:
	s_waitcnt lgkmcnt(0)
	s_cmpk_gt_u32 s17, 0x54
	s_cselect_b64 s[24:25], -1, 0
	s_and_b64 vcc, exec, s[24:25]
	s_barrier
	s_cbranch_vccnz .LBB0_127
	s_and_b32 s19, s8, 3
	s_mulk_i32 s19, 0x6000
	s_add_i32 s19, s19, s88
	s_mov_b32 m0, s19
	s_nop 0
	global_load_lds_dwordx4 v126, s[90:91]
	s_add_i32 m0, s19, 0x2000
	s_nop 0
	global_load_lds_dwordx4 v128, s[90:91]
	s_add_i32 m0, s19, 0x4000
	s_nop 0
	global_load_lds_dwordx4 v130, s[92:93]
	s_add_u32 s90, s90, 64
	s_addc_u32 s91, s91, 0
	s_add_u32 s92, s92, 64
	s_addc_u32 s93, s93, 0

.LBB0_131:
	s_waitcnt lgkmcnt(0)
	s_cmpk_gt_u32 s17, 0x53
	s_barrier
	s_cbranch_scc1 .LBB0_133
	s_add_i32 s19, s19, s88
	s_mov_b32 m0, s19
	s_nop 0
	global_load_lds_dwordx4 v126, s[90:91]
	s_add_i32 m0, s19, 0x2000
	s_nop 0
	global_load_lds_dwordx4 v128, s[90:91]
	s_add_i32 m0, s19, 0x4000
	s_nop 0
	global_load_lds_dwordx4 v130, s[92:93]
	s_add_u32 s90, s90, 64
	s_addc_u32 s91, s91, 0
	s_add_u32 s92, s92, 64
	s_addc_u32 s93, s93, 0

.LBB0_179:
	s_lshl_b32 s17, s8, 6
	v_mov_b32_e32 v10, v202
	s_and_b32 s17, s17, 0x1f00
	s_add_i32 s19, s17, 0xffffff00
	v_bfe_u32 v196, v10, 4, 2
	v_ashrrev_i32_e32 v197, 6, v10
	v_bfe_u32 v4, v10, 2, 4
	v_bitop3_b32 v0, v196, v10, 3 bitop3:0x78
	v_readlane_b32 s20, v254, 49
	v_or_b32_e32 v11, s19, v4
	v_lshlrev_b32_e32 v0, 4, v0
	v_or_b32_e32 v12, s22, v4
	v_readlane_b32 s21, v254, 50
	v_cmp_gt_i32_e32 vcc, 16, v197
	v_lshl_add_u64 v[2:3], s[40:41], 0, v[0:1]
	v_lshl_add_u64 v[4:5], s[20:21], 0, v[0:1]
	v_lshlrev_b32_e32 v0, 4, v197
	v_cndmask_b32_e32 v8, v11, v12, vcc
	v_add_u32_e32 v8, v8, v0
	v_ashrrev_i32_e32 v9, 31, v8
	v_cndmask_b32_e32 v7, v3, v5, vcc
	v_cndmask_b32_e32 v6, v2, v4, vcc
	v_lshlrev_b64 v[8:9], 11, v[8:9]
	v_cmp_gt_i32_e32 vcc, 8, v197
	v_lshl_add_u64 v[186:187], v[6:7], 0, v[8:9]
	s_movk_i32 s19, 0x80
	v_cndmask_b32_e32 v8, v11, v12, vcc
	v_add3_u32 v8, v0, v8, s19
	v_ashrrev_i32_e32 v9, 31, v8
	v_cndmask_b32_e32 v7, v3, v5, vcc
	v_cndmask_b32_e32 v6, v2, v4, vcc
	v_lshlrev_b64 v[8:9], 11, v[8:9]
	v_cmp_gt_i32_e32 vcc, 0, v197
	v_lshl_add_u64 v[188:189], v[6:7], 0, v[8:9]
	s_movk_i32 s19, 0x100
	v_cndmask_b32_e32 v8, v11, v12, vcc
	v_add3_u32 v8, v0, v8, s19
	v_ashrrev_i32_e32 v9, 31, v8
	v_cndmask_b32_e32 v7, v3, v5, vcc
	v_cndmask_b32_e32 v6, v2, v4, vcc
	v_lshlrev_b64 v[8:9], 11, v[8:9]
	v_cmp_gt_i32_e32 vcc, -8, v197
	v_and_b32_e32 v194, 63, v10
	v_lshl_add_u64 v[190:191], v[6:7], 0, v[8:9]
	v_cndmask_b32_e32 v6, v11, v12, vcc
	s_movk_i32 s19, 0x180
	v_cndmask_b32_e32 v2, v2, v4, vcc
	v_add3_u32 v4, v0, v6, s19
	v_lshlrev_b32_e32 v0, 4, v194
	v_lshl_or_b32 v198, v197, 10, v0
	v_add_u32_e32 v0, 0x2000, v198
	v_readfirstlane_b32 s19, v198
	s_mov_b32 m0, s19
	v_readfirstlane_b32 s19, v0
	v_add_u32_e32 v0, 0x4000, v198
	v_cndmask_b32_e32 v3, v3, v5, vcc
	v_ashrrev_i32_e32 v5, 31, v4
	s_barrier
	global_load_lds_dwordx4 v[186:187], off
	s_mov_b32 m0, s19
	v_readfirstlane_b32 s19, v0
	v_add_u32_e32 v0, 0x6000, v198
	v_lshlrev_b64 v[4:5], 11, v[4:5]
	global_load_lds_dwordx4 v[188:189], off
	s_mov_b32 m0, s19
	v_readfirstlane_b32 s19, v0
	v_add_u32_e32 v0, 0x8000, v198
	v_lshl_add_u64 v[192:193], v[2:3], 0, v[4:5]
	global_load_lds_dwordx4 v[190:191], off
	s_mov_b32 m0, s19
	v_readfirstlane_b32 s19, v0
	v_add_u32_e32 v0, 0xa000, v198
	global_load_lds_dwordx4 v[192:193], off
	v_lshl_add_u64 v[2:3], v[186:187], 0, 64
	s_mov_b32 m0, s19
	v_readfirstlane_b32 s19, v0
	v_add_u32_e32 v0, 0xc000, v198
	global_load_lds_dwordx4 v[2:3], off
	v_lshl_add_u64 v[2:3], v[188:189], 0, 64
	s_mov_b32 m0, s19
	v_readfirstlane_b32 s19, v0
	v_add_u32_e32 v0, 0xe000, v198
	global_load_lds_dwordx4 v[2:3], off
	v_lshl_add_u64 v[2:3], v[190:191], 0, 64
	s_mov_b32 m0, s19
	v_readfirstlane_b32 s19, v0
	v_add_u32_e32 v0, 0x10000, v198
	global_load_lds_dwordx4 v[2:3], off
	v_lshl_add_u64 v[2:3], v[192:193], 0, 64
	s_mov_b32 m0, s19
	v_readfirstlane_b32 s19, v0
	v_add_u32_e32 v0, 0x12000, v198
	global_load_lds_dwordx4 v[2:3], off
	v_lshl_add_u64 v[2:3], v[186:187], 0, s[10:11]
	s_mov_b32 m0, s19
	v_readfirstlane_b32 s19, v0
	v_add_u32_e32 v0, 0x14000, v198
	global_load_lds_dwordx4 v[2:3], off
	v_lshl_add_u64 v[2:3], v[188:189], 0, s[10:11]
	s_mov_b32 m0, s19
	v_readfirstlane_b32 s19, v0
	v_add_u32_e32 v0, 0x16000, v198
	global_load_lds_dwordx4 v[2:3], off
	v_lshl_add_u64 v[2:3], v[190:191], 0, s[10:11]
	s_mov_b32 m0, s19
	v_readfirstlane_b32 s19, v0
	global_load_lds_dwordx4 v[2:3], off
	v_lshl_add_u64 v[2:3], v[192:193], 0, s[10:11]
	s_mov_b32 m0, s19
	v_and_b32_e32 v199, 15, v10
	global_load_lds_dwordx4 v[2:3], off
	v_readfirstlane_b32 s90, v186
	v_readfirstlane_b32 s91, v187
	v_readfirstlane_b32 s92, v190
	v_readfirstlane_b32 s93, v191
	v_readfirstlane_b32 s88, v198
	s_nop 1
	v_subrev_u32_e32 v186, s90, v186
	v_subrev_u32_e32 v188, s90, v188
	v_subrev_u32_e32 v190, s92, v190
	v_subrev_u32_e32 v192, s92, v192
	s_add_u32 s90, s90, 0xc0
	s_addc_u32 s91, s91, 0
	s_add_u32 s92, s92, 0xc0
	s_addc_u32 s93, s93, 0
	v_bfe_u32 v2, v10, 2, 2
	v_xor_b32_e32 v2, v196, v2
	v_lshlrev_b32_e32 v3, 6, v199
	v_ashrrev_i32_e32 v0, 7, v10
	v_and_b32_e32 v195, 1, v197
	v_lshl_or_b32 v2, v2, 4, v3
	s_waitcnt vmcnt(8)
	v_lshl_or_b32 v200, v0, 12, v2
	v_lshlrev_b32_e32 v3, 13, v195
	s_movk_i32 s19, 0x4000
	s_waitcnt lgkmcnt(0)
	s_barrier
	ds_read_b128 v[122:125], v200
	ds_read_b128 v[126:129], v200 offset:1024
	ds_read_b128 v[130:133], v200 offset:2048
	ds_read_b128 v[134:137], v200 offset:3072
	v_or3_b32 v201, v3, v2, s19
	ds_read_b128 v[150:153], v201
	ds_read_b128 v[146:149], v201 offset:1024
	ds_read_b128 v[142:145], v201 offset:2048
	ds_read_b128 v[138:141], v201 offset:3072
	v_cmp_lt_i32_e32 vcc, 3, v197
	s_and_saveexec_b64 s[20:21], vcc
	s_cbranch_execz .LBB0_181
	s_barrier

.LBB0_187:
	s_waitcnt lgkmcnt(0)
	s_cmp_gt_u32 s19, 28
	s_cselect_b64 s[26:27], -1, 0
	s_and_b64 vcc, exec, s[26:27]
	s_barrier
	s_cbranch_vccnz .LBB0_189
	s_and_b32 s28, s31, 0x18000
	s_add_i32 s28, s28, s88
	s_mov_b32 m0, s28
	s_nop 0
	global_load_lds_dwordx4 v186, s[90:91]
	s_add_i32 m0, s28, 0x2000
	s_nop 0
	global_load_lds_dwordx4 v188, s[90:91]
	s_add_i32 m0, s28, 0x4000
	s_nop 0
	global_load_lds_dwordx4 v190, s[92:93]
	s_add_i32 m0, s28, 0x6000
	s_nop 0
	global_load_lds_dwordx4 v192, s[92:93]
	s_add_u32 s90, s90, 64
	s_addc_u32 s91, s91, 0
	s_add_u32 s92, s92, 64
	s_addc_u32 s93, s93, 0

.LBB0_193:
	s_waitcnt lgkmcnt(0)
	s_cmp_gt_u32 s19, 27
	s_barrier
	s_cbranch_scc1 .LBB0_195
	s_add_i32 s26, s34, s88
	s_mov_b32 m0, s26
	s_nop 0
	global_load_lds_dwordx4 v186, s[90:91]
	s_add_i32 m0, s26, 0x2000
	s_nop 0
	global_load_lds_dwordx4 v188, s[90:91]
	s_add_i32 m0, s26, 0x4000
	s_nop 0
	global_load_lds_dwordx4 v190, s[92:93]
	s_add_i32 m0, s26, 0x6000
	s_nop 0
	global_load_lds_dwordx4 v192, s[92:93]
	s_add_u32 s90, s90, 64
	s_addc_u32 s91, s91, 0
	s_add_u32 s92, s92, 64
	s_addc_u32 s93, s93, 0

.LBB0_285:
	s_andn2_b64 vcc, exec, s[22:23]
	s_cbranch_vccnz .LBB0_372
	v_readlane_b32 s22, v254, 44
	v_readlane_b32 s23, v254, 45
	s_andn2_b64 vcc, exec, s[22:23]
	s_cbranch_vccnz .LBB0_372
	v_mov_b32_e32 v10, v202
	v_readlane_b32 s8, v254, 48
	v_bfe_u32 v135, v10, 4, 2
	v_bitop3_b32 v0, v135, v10, 3 bitop3:0x78
	v_bfe_u32 v4, v10, 2, 4
	v_lshlrev_b32_e32 v0, 4, v0
	v_ashrrev_i32_e32 v136, 6, v10
	v_or_b32_e32 v11, s8, v4
	v_lshl_add_u64 v[2:3], s[20:21], 0, v[0:1]
	v_readlane_b32 s8, v254, 46
	v_readlane_b32 s20, v254, 49
	v_readlane_b32 s21, v254, 50
	v_or_b32_e32 v12, s8, v4
	v_cmp_gt_i32_e32 vcc, 16, v136
	v_lshl_add_u64 v[4:5], s[20:21], 0, v[0:1]
	v_lshlrev_b32_e32 v0, 4, v136
	v_cndmask_b32_e32 v8, v11, v12, vcc
	v_add_u32_e32 v8, v8, v0
	v_ashrrev_i32_e32 v9, 31, v8
	v_cndmask_b32_e32 v7, v3, v5, vcc
	v_cndmask_b32_e32 v6, v2, v4, vcc
	v_lshlrev_b64 v[8:9], 11, v[8:9]
	v_cmp_gt_i32_e32 vcc, 8, v136
	v_lshl_add_u64 v[126:127], v[6:7], 0, v[8:9]
	s_movk_i32 s8, 0x80
	v_cndmask_b32_e32 v8, v11, v12, vcc
	v_add3_u32 v8, v0, v8, s8
	v_ashrrev_i32_e32 v9, 31, v8
	v_cndmask_b32_e32 v7, v3, v5, vcc
	v_cndmask_b32_e32 v6, v2, v4, vcc
	v_lshlrev_b64 v[8:9], 11, v[8:9]
	v_cmp_gt_i32_e32 vcc, 0, v136
	v_and_b32_e32 v134, 63, v10
	v_lshl_add_u64 v[128:129], v[6:7], 0, v[8:9]
	v_cndmask_b32_e32 v6, v11, v12, vcc
	s_movk_i32 s8, 0x100
	v_cndmask_b32_e32 v2, v2, v4, vcc
	v_add3_u32 v4, v0, v6, s8
	v_lshlrev_b32_e32 v0, 4, v134
	v_lshl_or_b32 v137, v136, 10, v0
	v_add_u32_e32 v0, 0x2000, v137
	v_readfirstlane_b32 s8, v137
	v_cndmask_b32_e32 v3, v3, v5, vcc
	v_ashrrev_i32_e32 v5, 31, v4
	s_mov_b32 m0, s8
	v_readfirstlane_b32 s8, v0
	v_add_u32_e32 v0, 0x4000, v137
	v_lshlrev_b64 v[4:5], 11, v[4:5]
	s_barrier
	global_load_lds_dwordx4 v[126:127], off
	s_mov_b32 m0, s8
	v_readfirstlane_b32 s8, v0
	v_add_u32_e32 v0, 0x6000, v137
	v_lshl_add_u64 v[130:131], v[2:3], 0, v[4:5]
	global_load_lds_dwordx4 v[128:129], off
	s_mov_b32 m0, s8
	v_readfirstlane_b32 s8, v0
	v_add_u32_e32 v0, 0x8000, v137
	global_load_lds_dwordx4 v[130:131], off
	v_lshl_add_u64 v[2:3], v[126:127], 0, 64
	s_mov_b32 m0, s8
	v_readfirstlane_b32 s8, v0
	v_add_u32_e32 v0, 0xa000, v137
	global_load_lds_dwordx4 v[2:3], off
	v_lshl_add_u64 v[2:3], v[128:129], 0, 64
	s_mov_b32 m0, s8
	v_readfirstlane_b32 s8, v0
	v_add_u32_e32 v0, 0xc000, v137
	global_load_lds_dwordx4 v[2:3], off
	v_lshl_add_u64 v[2:3], v[130:131], 0, 64
	s_mov_b32 m0, s8
	v_readfirstlane_b32 s8, v0
	v_add_u32_e32 v0, 0xe000, v137
	global_load_lds_dwordx4 v[2:3], off
	v_lshl_add_u64 v[2:3], v[126:127], 0, s[10:11]
	s_mov_b32 m0, s8
	v_readfirstlane_b32 s8, v0
	v_add_u32_e32 v0, 0x10000, v137
	global_load_lds_dwordx4 v[2:3], off
	v_lshl_add_u64 v[2:3], v[128:129], 0, s[10:11]
	s_mov_b32 m0, s8
	v_readfirstlane_b32 s8, v0
	global_load_lds_dwordx4 v[2:3], off
	v_lshl_add_u64 v[2:3], v[130:131], 0, s[10:11]
	s_mov_b32 m0, s8
	v_and_b32_e32 v138, 15, v10
	global_load_lds_dwordx4 v[2:3], off
	v_readfirstlane_b32 s44, v126
	v_readfirstlane_b32 s45, v127
	v_readfirstlane_b32 s30, v130
	v_readfirstlane_b32 s31, v131
	v_readfirstlane_b32 s29, v137
	s_nop 1
	v_subrev_u32_e32 v126, s44, v126
	v_subrev_u32_e32 v128, s44, v128
	v_subrev_u32_e32 v130, s30, v130
	s_add_u32 s44, s44, 0xc0
	s_addc_u32 s45, s45, 0
	s_add_u32 s30, s30, 0xc0
	s_addc_u32 s31, s31, 0
	v_bfe_u32 v2, v10, 2, 2
	v_and_b32_e32 v139, 1, v136
	v_xor_b32_e32 v2, v135, v2
	v_lshlrev_b32_e32 v3, 6, v138
	v_ashrrev_i32_e32 v0, 7, v10
	v_lshl_or_b32 v2, v2, 4, v3
	v_lshlrev_b32_e32 v3, 12, v139
	s_movk_i32 s8, 0x4000
	s_waitcnt vmcnt(6)
	v_lshl_or_b32 v140, v0, 12, v2
	v_or3_b32 v141, v3, v2, s8
	s_waitcnt lgkmcnt(0)
	s_barrier
	ds_read_b128 v[2:5], v140
	ds_read_b128 v[6:9], v140 offset:1024
	ds_read_b128 v[10:13], v140 offset:2048
	ds_read_b128 v[14:17], v140 offset:3072
	ds_read_b128 v[26:29], v141
	ds_read_b128 v[22:25], v141 offset:1024
	v_cmp_lt_i32_e32 vcc, 3, v136
	s_and_saveexec_b64 s[20:21], vcc
	s_cbranch_execz .LBB0_289
	s_barrier

.LBB0_295:
	s_waitcnt lgkmcnt(0)
	s_cmp_gt_u32 s17, 28
	s_cselect_b64 s[24:25], -1, 0
	s_and_b64 vcc, exec, s[24:25]
	s_barrier
	s_cbranch_vccnz .LBB0_297
	s_and_b32 s19, s8, 3
	s_mulk_i32 s19, 0x6000
	s_add_i32 s19, s19, s29
	s_mov_b32 m0, s19
	s_nop 0
	global_load_lds_dwordx4 v126, s[44:45]
	s_add_i32 m0, s19, 0x2000
	s_nop 0
	global_load_lds_dwordx4 v128, s[44:45]
	s_add_i32 m0, s19, 0x4000
	s_nop 0
	global_load_lds_dwordx4 v130, s[30:31]
	s_add_u32 s44, s44, 64
	s_addc_u32 s45, s45, 0
	s_add_u32 s30, s30, 64
	s_addc_u32 s31, s31, 0

.LBB0_301:
	s_waitcnt lgkmcnt(0)
	s_cmp_gt_u32 s17, 27
	s_barrier
	s_cbranch_scc1 .LBB0_303
	s_add_i32 s19, s19, s29
	s_mov_b32 m0, s19
	s_nop 0
	global_load_lds_dwordx4 v126, s[44:45]
	s_add_i32 m0, s19, 0x2000
	s_nop 0
	global_load_lds_dwordx4 v128, s[44:45]
	s_add_i32 m0, s19, 0x4000
	s_nop 0
	global_load_lds_dwordx4 v130, s[30:31]
	s_add_u32 s44, s44, 64
	s_addc_u32 s45, s45, 0
	s_add_u32 s30, s30, 64
	s_addc_u32 s31, s31, 0

.LBB0_403:
	s_andn2_b64 vcc, exec, s[22:23]
	s_cbranch_vccnz .LBB0_428
	v_readlane_b32 s22, v254, 44
	v_readlane_b32 s23, v254, 45
	s_andn2_b64 vcc, exec, s[22:23]
	s_cbranch_vccnz .LBB0_428
	v_mov_b32_e32 v8, v202
	v_readlane_b32 s8, v254, 48
	v_bfe_u32 v201, v8, 4, 2
	v_bitop3_b32 v0, v201, v8, 3 bitop3:0x78
	v_bfe_u32 v4, v8, 2, 4
	v_lshlrev_b32_e32 v0, 4, v0
	v_ashrrev_i32_e32 v230, 6, v8
	v_or_b32_e32 v9, s8, v4
	v_lshl_add_u64 v[2:3], s[20:21], 0, v[0:1]
	v_readlane_b32 s8, v254, 46
	v_readlane_b32 s20, v254, 55
	v_readlane_b32 s21, v254, 56
	v_or_b32_e32 v10, s8, v4
	v_cmp_gt_i32_e32 vcc, 16, v230
	v_lshl_add_u64 v[4:5], s[20:21], 0, v[0:1]
	v_lshlrev_b32_e32 v0, 4, v230
	v_cndmask_b32_e32 v11, v9, v10, vcc
	v_cndmask_b32_e32 v7, v3, v5, vcc
	v_cndmask_b32_e32 v6, v2, v4, vcc
	v_add_u32_e32 v11, v11, v0
	v_cmp_gt_i32_e32 vcc, 8, v230
	v_mad_i64_i32 v[126:127], s[20:21], v11, s84, v[6:7]
	s_nop 0
	v_cndmask_b32_e32 v11, v9, v10, vcc
	s_movk_i32 s8, 0x80
	v_cndmask_b32_e32 v7, v3, v5, vcc
	v_cndmask_b32_e32 v6, v2, v4, vcc
	v_add3_u32 v11, v0, v11, s8
	v_cmp_gt_i32_e32 vcc, 0, v230
	v_mad_i64_i32 v[128:129], s[20:21], v11, s84, v[6:7]
	s_nop 0
	v_cndmask_b32_e32 v6, v9, v10, vcc
	s_movk_i32 s8, 0x100
	v_and_b32_e32 v200, 63, v8
	v_cndmask_b32_e32 v3, v3, v5, vcc
	v_cndmask_b32_e32 v2, v2, v4, vcc
	v_add3_u32 v0, v0, v6, s8
	v_mad_i64_i32 v[130:131], s[20:21], v0, s84, v[2:3]
	v_lshlrev_b32_e32 v0, 4, v200
	v_lshl_or_b32 v232, v230, 10, v0
	v_add_u32_e32 v0, 0x2000, v232
	v_readfirstlane_b32 s8, v232
	s_mov_b32 m0, s8
	v_readfirstlane_b32 s8, v0
	v_add_u32_e32 v0, 0x4000, v232
	s_barrier
	global_load_lds_dwordx4 v[126:127], off
	s_mov_b32 m0, s8
	v_readfirstlane_b32 s8, v0
	v_add_u32_e32 v0, 0x6000, v232
	global_load_lds_dwordx4 v[128:129], off
	s_mov_b32 m0, s8
	v_readfirstlane_b32 s8, v0
	v_add_u32_e32 v0, 0x8000, v232
	global_load_lds_dwordx4 v[130:131], off
	v_lshl_add_u64 v[2:3], v[126:127], 0, 64
	s_mov_b32 m0, s8
	v_readfirstlane_b32 s8, v0
	v_add_u32_e32 v0, 0xa000, v232
	global_load_lds_dwordx4 v[2:3], off
	v_lshl_add_u64 v[2:3], v[128:129], 0, 64
	s_mov_b32 m0, s8
	v_readfirstlane_b32 s8, v0
	v_add_u32_e32 v0, 0xc000, v232
	global_load_lds_dwordx4 v[2:3], off
	v_lshl_add_u64 v[2:3], v[130:131], 0, 64
	s_mov_b32 m0, s8
	v_readfirstlane_b32 s8, v0
	v_add_u32_e32 v0, 0xe000, v232
	global_load_lds_dwordx4 v[2:3], off
	v_lshl_add_u64 v[2:3], v[126:127], 0, s[10:11]
	s_mov_b32 m0, s8
	v_readfirstlane_b32 s8, v0
	v_add_u32_e32 v0, 0x10000, v232
	global_load_lds_dwordx4 v[2:3], off
	v_lshl_add_u64 v[2:3], v[128:129], 0, s[10:11]
	s_mov_b32 m0, s8
	v_readfirstlane_b32 s8, v0
	global_load_lds_dwordx4 v[2:3], off
	v_lshl_add_u64 v[2:3], v[130:131], 0, s[10:11]
	s_mov_b32 m0, s8
	v_and_b32_e32 v234, 15, v8
	global_load_lds_dwordx4 v[2:3], off
	v_readfirstlane_b32 s90, v126
	v_readfirstlane_b32 s91, v127
	v_readfirstlane_b32 s92, v130
	v_readfirstlane_b32 s93, v131
	v_readfirstlane_b32 s88, v232
	s_nop 1
	v_subrev_u32_e32 v126, s90, v126
	v_subrev_u32_e32 v128, s90, v128
	v_subrev_u32_e32 v130, s92, v130
	s_add_u32 s90, s90, 0xc0
	s_addc_u32 s91, s91, 0
	s_add_u32 s92, s92, 0xc0
	s_addc_u32 s93, s93, 0
	v_bfe_u32 v2, v8, 2, 2
	v_and_b32_e32 v231, 1, v230
	v_xor_b32_e32 v2, v201, v2
	v_lshlrev_b32_e32 v3, 6, v234
	v_ashrrev_i32_e32 v0, 7, v8
	v_lshl_or_b32 v2, v2, 4, v3
	v_lshlrev_b32_e32 v3, 12, v231
	s_movk_i32 s8, 0x4000
	s_waitcnt vmcnt(6)
	v_lshl_or_b32 v235, v0, 12, v2
	v_or3_b32 v236, v3, v2, s8
	s_waitcnt lgkmcnt(0)
	s_barrier
	ds_read_b128 v[14:17], v235
	ds_read_b128 v[10:13], v235 offset:1024
	ds_read_b128 v[6:9], v235 offset:2048
	ds_read_b128 v[2:5], v235 offset:3072
	ds_read_b128 v[26:29], v236
	ds_read_b128 v[18:21], v236 offset:1024
	v_cmp_lt_i32_e32 vcc, 3, v230
	s_and_saveexec_b64 s[20:21], vcc
	s_cbranch_execz .LBB0_407
	s_barrier

.LBB0_413:
	s_waitcnt lgkmcnt(0)
	s_cmp_gt_u32 s17, 44
	s_cselect_b64 s[24:25], -1, 0
	s_and_b64 vcc, exec, s[24:25]
	s_barrier
	s_cbranch_vccnz .LBB0_415
	s_and_b32 s19, s8, 3
	s_mulk_i32 s19, 0x6000
	s_add_i32 s19, s19, s88
	s_mov_b32 m0, s19
	s_nop 0
	global_load_lds_dwordx4 v126, s[90:91]
	s_add_i32 m0, s19, 0x2000
	s_nop 0
	global_load_lds_dwordx4 v128, s[90:91]
	s_add_i32 m0, s19, 0x4000
	s_nop 0
	global_load_lds_dwordx4 v130, s[92:93]
	s_add_u32 s90, s90, 64
	s_addc_u32 s91, s91, 0
	s_add_u32 s92, s92, 64
	s_addc_u32 s93, s93, 0

.LBB0_419:
	s_waitcnt lgkmcnt(0)
	s_cmp_gt_u32 s17, 43
	s_barrier
	s_cbranch_scc1 .LBB0_421
	s_add_i32 s24, s28, s88
	s_mov_b32 m0, s24
	s_nop 0
	global_load_lds_dwordx4 v126, s[90:91]
	s_add_i32 m0, s24, 0x2000
	s_nop 0
	global_load_lds_dwordx4 v128, s[90:91]
	s_add_i32 m0, s24, 0x4000
	s_nop 0
	global_load_lds_dwordx4 v130, s[92:93]
	s_add_u32 s90, s90, 64
	s_addc_u32 s91, s91, 0
	s_add_u32 s92, s92, 64
	s_addc_u32 s93, s93, 0

.LBB0_641:
	s_lshl_b32 s19, s17, 6
	s_and_b32 s19, s19, 0x1f00
	v_mov_b32_e32 v200, v202
	s_add_i32 s20, s19, 0xffffff00
	v_bfe_u32 v186, v200, 2, 4
	v_bfe_u32 v197, v200, 4, 2
	v_or_b32_e32 v10, s20, v186
	v_readlane_b32 s20, v254, 46
	v_ashrrev_i32_e32 v187, 6, v200
	v_bitop3_b32 v0, v197, v200, 3 bitop3:0x78
	v_or_b32_e32 v11, s20, v186
	v_readlane_b32 s20, v254, 49
	v_lshlrev_b32_e32 v0, 4, v0
	v_readlane_b32 s21, v254, 50
	v_cmp_gt_i32_e32 vcc, 16, v187
	v_lshl_add_u64 v[2:3], s[44:45], 0, v[0:1]
	v_lshl_add_u64 v[4:5], s[20:21], 0, v[0:1]
	v_lshlrev_b32_e32 v0, 4, v187
	v_cndmask_b32_e32 v8, v10, v11, vcc
	v_add_u32_e32 v8, v8, v0
	v_ashrrev_i32_e32 v9, 31, v8
	v_cndmask_b32_e32 v7, v3, v5, vcc
	v_cndmask_b32_e32 v6, v2, v4, vcc
	v_lshlrev_b64 v[8:9], 11, v[8:9]
	v_cmp_gt_i32_e32 vcc, 8, v187
	v_lshl_add_u64 v[188:189], v[6:7], 0, v[8:9]
	s_movk_i32 s20, 0x80
	v_cndmask_b32_e32 v8, v10, v11, vcc
	v_add3_u32 v8, v0, v8, s20
	v_ashrrev_i32_e32 v9, 31, v8
	v_cndmask_b32_e32 v7, v3, v5, vcc
	v_cndmask_b32_e32 v6, v2, v4, vcc
	v_lshlrev_b64 v[8:9], 11, v[8:9]
	v_cmp_gt_i32_e32 vcc, 0, v187
	v_lshl_add_u64 v[190:191], v[6:7], 0, v[8:9]
	s_movk_i32 s20, 0x100
	v_cndmask_b32_e32 v8, v10, v11, vcc
	v_add3_u32 v8, v0, v8, s20
	v_ashrrev_i32_e32 v9, 31, v8
	v_cndmask_b32_e32 v7, v3, v5, vcc
	v_cndmask_b32_e32 v6, v2, v4, vcc
	v_lshlrev_b64 v[8:9], 11, v[8:9]
	v_cmp_gt_i32_e32 vcc, -8, v187
	v_lshl_add_u64 v[192:193], v[6:7], 0, v[8:9]
	s_movk_i32 s20, 0x180
	v_cndmask_b32_e32 v6, v10, v11, vcc
	v_and_b32_e32 v196, 63, v200
	v_cndmask_b32_e32 v2, v2, v4, vcc
	v_add3_u32 v4, v0, v6, s20
	v_cndmask_b32_e32 v3, v3, v5, vcc
	v_ashrrev_i32_e32 v5, 31, v4
	v_lshlrev_b32_e32 v198, 4, v196
	v_lshlrev_b64 v[4:5], 11, v[4:5]
	v_lshl_or_b32 v0, v187, 10, v198
	v_lshl_add_u64 v[194:195], v[2:3], 0, v[4:5]
	v_readfirstlane_b32 s20, v0
	v_add_u32_e32 v2, 0x2000, v0
	s_mov_b32 m0, s20
	v_readfirstlane_b32 s20, v2
	v_add_u32_e32 v2, 0x4000, v0
	s_waitcnt lgkmcnt(0)
	s_barrier
	global_load_lds_dwordx4 v[188:189], off
	s_mov_b32 m0, s20
	v_readfirstlane_b32 s20, v2
	v_add_u32_e32 v2, 0x6000, v0
	global_load_lds_dwordx4 v[190:191], off
	s_mov_b32 m0, s20
	v_readfirstlane_b32 s20, v2
	v_add_u32_e32 v4, 0x8000, v0
	global_load_lds_dwordx4 v[192:193], off
	s_mov_b32 m0, s20
	v_readfirstlane_b32 s20, v4
	v_add_u32_e32 v4, 0xa000, v0
	global_load_lds_dwordx4 v[194:195], off
	v_lshl_add_u64 v[2:3], v[188:189], 0, 64
	s_mov_b32 m0, s20
	v_readfirstlane_b32 s20, v4
	v_add_u32_e32 v4, 0xc000, v0
	global_load_lds_dwordx4 v[2:3], off
	v_lshl_add_u64 v[2:3], v[190:191], 0, 64
	s_mov_b32 m0, s20
	v_readfirstlane_b32 s20, v4
	v_add_u32_e32 v4, 0xe000, v0
	global_load_lds_dwordx4 v[2:3], off
	v_lshl_add_u64 v[2:3], v[192:193], 0, 64
	s_mov_b32 m0, s20
	v_readfirstlane_b32 s20, v4
	v_add_u32_e32 v4, 0x10000, v0
	global_load_lds_dwordx4 v[2:3], off
	v_lshl_add_u64 v[2:3], v[194:195], 0, 64
	s_mov_b32 m0, s20
	v_readfirstlane_b32 s20, v4
	v_add_u32_e32 v4, 0x12000, v0
	global_load_lds_dwordx4 v[2:3], off
	v_lshl_add_u64 v[2:3], v[188:189], 0, s[10:11]
	s_mov_b32 m0, s20
	v_readfirstlane_b32 s20, v4
	v_add_u32_e32 v4, 0x14000, v0
	global_load_lds_dwordx4 v[2:3], off
	v_lshl_add_u64 v[2:3], v[190:191], 0, s[10:11]
	s_mov_b32 m0, s20
	v_readfirstlane_b32 s20, v4
	v_add_u32_e32 v4, 0x16000, v0
	global_load_lds_dwordx4 v[2:3], off
	v_lshl_add_u64 v[2:3], v[192:193], 0, s[10:11]
	s_mov_b32 m0, s20
	v_readfirstlane_b32 s20, v4
	global_load_lds_dwordx4 v[2:3], off
	v_lshl_add_u64 v[2:3], v[194:195], 0, s[10:11]
	s_mov_b32 m0, s20
	v_and_b32_e32 v199, 15, v200
	global_load_lds_dwordx4 v[2:3], off
	v_readfirstlane_b32 s94, v188
	v_readfirstlane_b32 s95, v189
	v_readfirstlane_b32 s42, v192
	v_readfirstlane_b32 s43, v193
	v_readfirstlane_b32 s69, v0
	s_nop 1
	v_subrev_u32_e32 v188, s94, v188
	v_subrev_u32_e32 v190, s94, v190
	v_subrev_u32_e32 v192, s42, v192
	v_subrev_u32_e32 v194, s42, v194
	s_add_u32 s94, s94, 0xc0
	s_addc_u32 s95, s95, 0
	s_add_u32 s42, s42, 0xc0
	s_addc_u32 s43, s43, 0
	v_bfe_u32 v2, v200, 2, 2
	v_xor_b32_e32 v2, v197, v2
	v_lshlrev_b32_e32 v3, 6, v199
	v_ashrrev_i32_e32 v230, 7, v200
	v_and_b32_e32 v201, 1, v187
	v_lshl_or_b32 v2, v2, 4, v3
	s_waitcnt vmcnt(8)
	v_lshl_or_b32 v231, v230, 12, v2
	v_lshlrev_b32_e32 v3, 13, v201
	s_movk_i32 s20, 0x4000
	s_waitcnt lgkmcnt(0)
	s_barrier
	ds_read_b128 v[130:133], v231
	ds_read_b128 v[134:137], v231 offset:1024
	ds_read_b128 v[138:141], v231 offset:2048
	ds_read_b128 v[142:145], v231 offset:3072
	v_or3_b32 v232, v3, v2, s20
	ds_read_b128 v[158:161], v232
	ds_read_b128 v[154:157], v232 offset:1024
	ds_read_b128 v[150:153], v232 offset:2048
	ds_read_b128 v[146:149], v232 offset:3072
	v_cmp_lt_i32_e32 vcc, 3, v187
	s_and_saveexec_b64 s[20:21], vcc
	s_cbranch_execz .LBB0_643
	s_barrier

.LBB0_649:
	s_waitcnt lgkmcnt(0)
	s_cmp_gt_u32 s30, 28
	s_cselect_b64 s[26:27], -1, 0
	s_and_b64 vcc, exec, s[26:27]
	s_barrier
	s_cbranch_vccnz .LBB0_651
	s_and_b32 s28, s31, 0x18000
	s_add_i32 s28, s28, s69
	s_mov_b32 m0, s28
	s_nop 0
	global_load_lds_dwordx4 v188, s[94:95]
	s_add_i32 m0, s28, 0x2000
	s_nop 0
	global_load_lds_dwordx4 v190, s[94:95]
	s_add_i32 m0, s28, 0x4000
	s_nop 0
	global_load_lds_dwordx4 v192, s[42:43]
	s_add_i32 m0, s28, 0x6000
	s_nop 0
	global_load_lds_dwordx4 v194, s[42:43]
	s_add_u32 s94, s94, 64
	s_addc_u32 s95, s95, 0
	s_add_u32 s42, s42, 64
	s_addc_u32 s43, s43, 0

.LBB0_655:
	s_waitcnt lgkmcnt(0)
	s_cmp_gt_u32 s30, 27
	s_barrier
	s_cbranch_scc1 .LBB0_657
	s_add_i32 s26, s34, s69
	s_mov_b32 m0, s26
	s_nop 0
	global_load_lds_dwordx4 v188, s[94:95]
	s_add_i32 m0, s26, 0x2000
	s_nop 0
	global_load_lds_dwordx4 v190, s[94:95]
	s_add_i32 m0, s26, 0x4000
	s_nop 0
	global_load_lds_dwordx4 v192, s[42:43]
	s_add_i32 m0, s26, 0x6000
	s_nop 0
	global_load_lds_dwordx4 v194, s[42:43]
	s_add_u32 s94, s94, 64
	s_addc_u32 s95, s95, 0
	s_add_u32 s42, s42, 64
	s_addc_u32 s43, s43, 0
